# XCD-local barriers: waiters poll the monotonic arrival counter (>= target) instead of the generation word; generation compares monotonic; local generation bump not waited
# speedup vs baseline: 1.0094x; 1.0041x over previous
.Lloc_d:
	v_readlane_b32 s2, v252, 49
	v_readlane_b32 s3, v252, 50
	s_waitcnt vmcnt(0)
	buffer_inv sc1
	s_nop 2
	global_atomic_add v197, v223, s[2:3]
	s_branch .LBB0_125

.LBB0_585:
	v_readlane_b32 s2, v252, 47
	v_readlane_b32 s3, v252, 48
	v_cvt_f32_u32_e32 v1, v2
	v_sub_u32_e32 v4, 0, v2
	v_rcp_iflag_f32_e32 v1, v1
	s_nop 1
	global_atomic_add v3, v197, v223, s[2:3] sc0
	v_mul_f32_e32 v1, 0x4f7ffffe, v1
	v_cvt_u32_f32_e32 v1, v1
	v_mul_lo_u32 v4, v4, v1
	v_mul_hi_u32 v4, v1, v4
	v_add_u32_e32 v1, v1, v4
	s_waitcnt vmcnt(0)
	v_mul_hi_u32 v1, v3, v1
	v_mul_lo_u32 v4, v1, v2
	v_sub_u32_e32 v4, v3, v4
	v_add_u32_e32 v5, 1, v1
	v_cmp_ge_u32_e32 vcc, v4, v2
	v_add_u32_e32 v3, 1, v3
	s_nop 0
	v_cndmask_b32_e32 v1, v1, v5, vcc
	v_sub_u32_e32 v5, v4, v2
	v_cndmask_b32_e32 v4, v4, v5, vcc
	v_add_u32_e32 v5, 1, v1
	v_cmp_ge_u32_e32 vcc, v4, v2
	s_nop 1
	v_cndmask_b32_e32 v1, v1, v5, vcc
	v_mul_lo_u32 v4, v2, v1
	v_add_u32_e32 v2, v4, v2
	v_cmp_ne_u32_e32 vcc, v3, v2
	s_and_saveexec_b64 s[2:3], vcc
	s_xor_b64 s[8:9], exec, s[2:3]
	s_cbranch_execz .LBB0_599
	buffer_inv sc1
	v_readlane_b32 s2, v252, 49
	v_readlane_b32 s3, v252, 50
	v_add_u32_e32 v5, 1, v1
	v_readlane_b32 s12, v248, 40
	s_cmp_eq_u32 s12, 0
	s_cbranch_scc1 .Lnl_g_a
	v_readlane_b32 s2, v252, 47
	v_readlane_b32 s3, v252, 48
	v_mov_b32_e32 v5, v2
.Lnl_g_a:
	v_writelane_b32 v248, s2, 42
	v_writelane_b32 v248, s3, 43
	s_waitcnt lgkmcnt(0)
	s_nop 3
	global_load_dword v0, v197, s[2:3] sc1
	s_waitcnt vmcnt(0)
	v_cmp_lt_u32_e32 vcc, v0, v5
	s_and_saveexec_b64 s[12:13], vcc
	s_cbranch_execz .LBB0_598
	s_mov_b32 s1, 1
	s_mov_b64 s[18:19], 0
	s_branch .LBB0_589

.LBB0_591:
	v_readlane_b32 s2, v248, 42
	v_readlane_b32 s3, v248, 43
	s_add_i32 s1, s1, 1
	s_mov_b64 s[24:25], -1
	s_nop 2
	global_load_dword v0, v197, s[2:3] sc1
	s_waitcnt vmcnt(0)
	v_cmp_ge_u32_e32 vcc, v0, v5
	s_orn2_b64 s[22:23], vcc, exec
	s_branch .LBB0_588

.LBB0_639:
	v_readlane_b32 s2, v252, 47
	v_readlane_b32 s3, v252, 48
	v_cvt_f32_u32_e32 v1, v2
	v_sub_u32_e32 v4, 0, v2
	v_rcp_iflag_f32_e32 v1, v1
	s_nop 1
	global_atomic_add v3, v197, v223, s[2:3] sc0
	v_mul_f32_e32 v1, 0x4f7ffffe, v1
	v_cvt_u32_f32_e32 v1, v1
	v_mul_lo_u32 v4, v4, v1
	v_mul_hi_u32 v4, v1, v4
	v_add_u32_e32 v1, v1, v4
	s_waitcnt vmcnt(0)
	v_mul_hi_u32 v1, v3, v1
	v_mul_lo_u32 v4, v1, v2
	v_sub_u32_e32 v4, v3, v4
	v_add_u32_e32 v5, 1, v1
	v_cmp_ge_u32_e32 vcc, v4, v2
	v_add_u32_e32 v3, 1, v3
	s_nop 0
	v_cndmask_b32_e32 v1, v1, v5, vcc
	v_sub_u32_e32 v5, v4, v2
	v_cndmask_b32_e32 v4, v4, v5, vcc
	v_add_u32_e32 v5, 1, v1
	v_cmp_ge_u32_e32 vcc, v4, v2
	s_nop 1
	v_cndmask_b32_e32 v1, v1, v5, vcc
	v_mul_lo_u32 v4, v2, v1
	v_add_u32_e32 v2, v4, v2
	v_cmp_ne_u32_e32 vcc, v3, v2
	s_and_saveexec_b64 s[2:3], vcc
	s_xor_b64 s[8:9], exec, s[2:3]
	s_cbranch_execz .LBB0_653
	buffer_inv sc1
	v_readlane_b32 s2, v252, 49
	v_readlane_b32 s3, v252, 50
	v_add_u32_e32 v5, 1, v1
	v_readlane_b32 s12, v248, 40
	s_cmp_eq_u32 s12, 0
	s_cbranch_scc1 .Lnl_g_b
	v_readlane_b32 s12, v249, 53
	s_cmp_eq_u32 s12, 1
	s_cbranch_scc1 .Lnl_g_b
	v_readlane_b32 s2, v252, 47
	v_readlane_b32 s3, v252, 48
	v_mov_b32_e32 v5, v2
.Lnl_g_b:
	v_writelane_b32 v248, s2, 42
	v_writelane_b32 v248, s3, 43
	s_waitcnt lgkmcnt(0)
	s_nop 3
	global_load_dword v0, v197, s[2:3] sc1
	s_waitcnt vmcnt(0)
	v_cmp_lt_u32_e32 vcc, v0, v5
	s_and_saveexec_b64 s[12:13], vcc
	s_cbranch_execz .LBB0_652
	s_mov_b32 s26, s30
	s_mov_b32 s1, 1
	s_mov_b64 s[18:19], 0
	s_branch .LBB0_643

.LBB0_895:
	v_readlane_b32 s2, v252, 47
	v_readlane_b32 s3, v252, 48
	v_cvt_f32_u32_e32 v1, v2
	v_sub_u32_e32 v4, 0, v2
	v_rcp_iflag_f32_e32 v1, v1
	s_nop 1
	global_atomic_add v3, v197, v223, s[2:3] sc0
	v_mul_f32_e32 v1, 0x4f7ffffe, v1
	v_cvt_u32_f32_e32 v1, v1
	v_mul_lo_u32 v4, v4, v1
	v_mul_hi_u32 v4, v1, v4
	v_add_u32_e32 v1, v1, v4
	s_waitcnt vmcnt(0)
	v_mul_hi_u32 v1, v3, v1
	v_mul_lo_u32 v4, v1, v2
	v_sub_u32_e32 v4, v3, v4
	v_add_u32_e32 v5, 1, v1
	v_cmp_ge_u32_e32 vcc, v4, v2
	v_add_u32_e32 v3, 1, v3
	s_nop 0
	v_cndmask_b32_e32 v1, v1, v5, vcc
	v_sub_u32_e32 v5, v4, v2
	v_cndmask_b32_e32 v4, v4, v5, vcc
	v_add_u32_e32 v5, 1, v1
	v_cmp_ge_u32_e32 vcc, v4, v2
	s_nop 1
	v_cndmask_b32_e32 v1, v1, v5, vcc
	v_mul_lo_u32 v4, v2, v1
	v_add_u32_e32 v2, v4, v2
	v_cmp_ne_u32_e32 vcc, v3, v2
	s_and_saveexec_b64 s[2:3], vcc
	s_xor_b64 s[8:9], exec, s[2:3]
	s_cbranch_execz .LBB0_909
	buffer_inv sc1
	v_readlane_b32 s2, v252, 49
	v_readlane_b32 s3, v252, 50
	v_add_u32_e32 v5, 1, v1
	v_readlane_b32 s12, v248, 40
	s_cmp_eq_u32 s12, 0
	s_cbranch_scc1 .Lnl_g_d
	v_readlane_b32 s12, v249, 53
	s_cmp_eq_u32 s12, 1
	s_cbranch_scc1 .Lnl_l_d
	s_cmp_lg_u32 s12, 0
	s_cbranch_scc1 .Lnl_g_d
	v_readlane_b32 s12, v249, 21
	s_cmp_gt_u32 s12, 1
	s_cbranch_scc0 .Lnl_g_d
.Lnl_l_d:
	v_readlane_b32 s2, v252, 47
	v_readlane_b32 s3, v252, 48
	v_mov_b32_e32 v5, v2
.Lnl_g_d:
	v_writelane_b32 v248, s2, 42
	v_writelane_b32 v248, s3, 43
	s_waitcnt lgkmcnt(0)
	s_nop 3
	global_load_dword v0, v197, s[2:3] sc1
	s_waitcnt vmcnt(0)
	v_cmp_lt_u32_e32 vcc, v0, v5
	s_and_saveexec_b64 s[12:13], vcc
	s_cbranch_execz .LBB0_908
	s_mov_b32 s26, s30
	s_mov_b32 s2, 1
	s_mov_b64 s[18:19], 0
	s_branch .LBB0_899

.LBB0_901:
	v_readlane_b32 s14, v248, 42
	v_readlane_b32 s15, v248, 43
	s_add_i32 s2, s2, 1
	s_mov_b64 s[24:25], -1
	s_nop 2
	global_load_dword v0, v197, s[14:15] sc1
	s_waitcnt vmcnt(0)
	v_cmp_ge_u32_e32 vcc, v0, v5
	s_orn2_b64 s[22:23], vcc, exec
	s_branch .LBB0_898
